# attention loop: next-tile global loads and pointer increments issued inside the QK MFMA stream (active waves), on top of v32
# speedup vs baseline: 1.0072x; 1.0072x over previous
; template <int DQK, bool MLA> ...
;     ...
;     auto substep = [&](f32x16& a, f32x16& b, int knext_ofs, int vofs, int h, int kafter_ofs) __attribute__((always_inline)) {
;         const LAS unsigned char* kb = lds + knext_ofs + r32 * KPITCH + hi * 16;
;         const LAS unsigned char* vb = lds + vofs + r32 * 144 + hi * 16 + h * 64;
;         u32x4 pw0, pw1; bf16x8 vf0[4], vf1[4], kr[3];
;         kr[0] = kp0; kr[1] = kp1;
;         float rs0 = rs_early;
;         __builtin_amdgcn_sched_barrier(0);
; #pragma unroll
;         for (int d0 = 0; d0 < KS; ++d0) {
;             if (d0 + 2 < KS) kr[(d0 + 2) % 3] = *(const LAS bf16x8*)(kb + (d0 + 2) * 32);
;             if (d0 == KS - 3) {
; #pragma unroll
;                 for (int d = 0; d < 4; ++d) vf0[d] = *(const LAS bf16x8*)(vb + d * 4608);
;             }
;             if (d0 == 0) { const f32x16 z16 = {0.f, 0.f, 0.f, 0.f, 0.f, 0.f, 0.f, 0.f, 0.f, 0.f, 0.f, 0.f, 0.f, 0.f, 0.f, 0.f};
;                 b = __builtin_amdgcn_mfma_f32_32x32x16_bf16(kr[0], qf[0], z16, 0, 0, 0); }
;             else b = __builtin_amdgcn_mfma_f32_32x32x16_bf16(kr[d0 % 3], qf[d0], b, 0, 0, 0);
; #pragma unroll
;             for (int e = 6 + (10 * d0) / KS; e < 6 + (10 * (d0 + 1)) / KS; ++e) {
;                 const float x = __builtin_amdgcn_exp2f(a[e]);
;                 a[e] = x;
;                 rs0 += x;
;                 if (e == 7)  { pw0.x = pk(a[0], a[1]); pw0.y = pk(a[2], a[3]);   pw0.z = pk(a[4], a[5]);   pw0.w = pk(a[6], a[7]); }
;                 if (e == 15) { pw1.x = pk(a[8], a[9]); pw1.y = pk(a[10], a[11]); pw1.z = pk(a[12], a[13]); pw1.w = pk(a[14], a[15]); }
;             }
;             __builtin_amdgcn_sched_barrier(0);
;         }
;         l_run += rs0;
;         float rs_n = 0.f;
; #pragma unroll
;         for (int kk = 0; kk < 2; ++kk) {
;             if (kk == 0) {
; #pragma unroll
;                 for (int d = 0; d < 4; ++d) vf1[d] = *(const LAS bf16x8*)(vb + d * 4608 + 32);
;             } else { const LAS unsigned char* ka = lds + kafter_ofs + r32 * KPITCH + hi * 16; kp0 = *(const LAS bf16x8*)(ka); kp1 = *(const LAS bf16x8*)(ka + 32); }
;             const bf16x8 pb = __builtin_bit_cast(bf16x8, kk ? pw1 : pw0);
; #pragma unroll
;             for (int d = 0; d < 4; ++d) {
;                 o[d] = __builtin_amdgcn_mfma_f32_32x32x16_bf16(kk ? vf1[d] : vf0[d], pb, o[d], 0, 0, 0);
.LBB0_1041:
	s_mov_b32 s72, s71
	s_mov_b32 s71, s34
	s_cmp_gt_u32 s68, s48
	s_cbranch_scc1 .Lattn_inact
	s_bitcmp1_b32 s68, 0
	s_cselect_b32 s34, s87, 0x12c00
	v_add_u32_e32 v193, s70, v183
	v_add_u32_e32 v208, s34, v175
	s_waitcnt lgkmcnt(1)
	v_mfma_f32_32x32x16_bf16 v[80:95], v[80:83], v[100:103], 0
	ds_read_b128 v[210:213], v193 offset:12864
	global_load_dwordx4 v[148:151], v[204:205], off
	global_load_dwordx4 v[152:155], v[206:207], off
	v_lshl_add_u64 v[204:205], v[204:205], 0, s[14:15]
	v_lshl_add_u64 v[206:207], v[206:207], 0, s[14:15]
	s_waitcnt lgkmcnt(1)
	v_mfma_f32_32x32x16_bf16 v[80:95], v[160:163], v[104:107], v[80:95]
	v_exp_f32_e32 v70, v70
	ds_read_b128 v[214:217], v193 offset:12896
	v_add_f32_e32 v186, v70, v186
	v_lshl_add_u64 v[234:235], s[26:27], 0, v[202:203]
	global_load_dwordx4 v[156:159], v[234:235], off
	v_lshl_add_u64 v[202:203], v[202:203], 0, s[0:1]
	s_waitcnt lgkmcnt(1)
	v_mfma_f32_32x32x16_bf16 v[80:95], v[210:213], v[108:111], v[80:95]
	ds_read_b128 v[160:163], v193 offset:12928
	v_exp_f32_e32 v71, v71
	s_nop 0
	v_cvt_pk_bf16_f32 v64, v64, v65
	s_nop 0
	v_cvt_pk_bf16_f32 v65, v66, v67
	s_nop 0
	v_cvt_pk_bf16_f32 v66, v68, v69
	s_nop 0
	v_cvt_pk_bf16_f32 v67, v70, v71
	s_nop 0
	v_add_f32_e32 v186, v71, v186
	s_waitcnt lgkmcnt(1)
	v_mfma_f32_32x32x16_bf16 v[80:95], v[214:217], v[112:115], v[80:95]
	ds_read_b128 v[68:71], v193 offset:12960
	v_lshl_add_u64 v[234:235], s[26:27], 0, v[190:191]
	v_add_co_u32_e32 v236, vcc, 0x1d204000, v234
	s_nop 1
	v_addc_co_u32_e32 v237, vcc, 0, v235, vcc
	global_load_dwordx4 v[164:167], v[236:237], off offset:2048
	v_exp_f32_e32 v194, v72
	s_nop 0
	v_add_f32_e32 v72, v194, v186
	s_waitcnt lgkmcnt(1)
	v_mfma_f32_32x32x16_bf16 v[80:95], v[160:163], v[116:119], v[80:95]
	v_exp_f32_e32 v186, v73
	ds_read_b128 v[210:213], v193 offset:12992
	v_add_f32_e32 v72, v186, v72
	v_add_co_u32_e32 v236, vcc, 0x1d206000, v234
	s_nop 1
	v_addc_co_u32_e32 v237, vcc, 0, v235, vcc
	global_load_dwordx4 v[168:171], v[236:237], off offset:2048
	s_waitcnt lgkmcnt(1)
	v_mfma_f32_32x32x16_bf16 v[80:95], v[68:71], v[120:123], v[80:95]
	s_and_saveexec_b64 s[34:35], s[4:5]
	s_cbranch_execz .Lattn_ld6_skip
	v_add_co_u32_e32 v236, vcc, 0x1d208000, v234
	s_nop 1
	v_addc_co_u32_e32 v237, vcc, 0, v235, vcc
	global_load_dwordx4 v[96:99], v[236:237], off offset:2048
.Lattn_ld6_skip:
	s_or_b64 exec, exec, s[34:35]
	ds_read_b128 v[160:163], v193 offset:13024
	v_exp_f32_e32 v195, v74
	s_nop 0
	v_add_f32_e32 v72, v195, v72
	v_lshl_add_u64 v[190:191], v[190:191], 0, s[20:21]
	s_waitcnt lgkmcnt(1)
	v_mfma_f32_32x32x16_bf16 v[80:95], v[210:213], v[124:127], v[80:95]
	ds_read_b128 v[68:71], v193 offset:13056
	s_waitcnt lgkmcnt(1)
	v_mfma_f32_32x32x16_bf16 v[80:95], v[160:163], v[128:131], v[80:95]
	v_exp_f32_e32 v196, v75
	ds_read_b128 v[210:213], v193 offset:13088
	v_add_f32_e32 v160, v196, v72
	s_waitcnt lgkmcnt(1)
	v_mfma_f32_32x32x16_bf16 v[80:95], v[68:71], v[136:139], v[80:95]
	ds_read_b128 v[72:75], v193 offset:13120
	v_exp_f32_e32 v76, v76
	s_nop 0
	v_add_f32_e32 v197, v76, v160
	ds_read_b128 v[68:71], v193 offset:13152
	ds_read_b128 v[160:163], v208
	ds_read_b128 v[214:217], v208 offset:4608
	ds_read_b128 v[218:221], v208 offset:9216
	ds_read_b128 v[222:225], v208 offset:13824
	s_waitcnt lgkmcnt(6)
	v_mfma_f32_32x32x16_bf16 v[80:95], v[210:213], v[144:147], v[80:95]
	v_exp_f32_e32 v77, v77
	s_nop 0
	v_add_f32_e32 v193, v77, v197
	s_waitcnt lgkmcnt(5)
	v_mfma_f32_32x32x16_bf16 v[80:95], v[72:75], v[132:135], v[80:95]
	v_exp_f32_e32 v72, v78
	s_nop 0
	v_add_f32_e32 v73, v72, v193
	s_waitcnt lgkmcnt(4)
	v_mfma_f32_32x32x16_bf16 v[80:95], v[68:71], v[140:143], v[80:95]
	v_exp_f32_e32 v71, v79
	s_nop 0
	v_cvt_pk_bf16_f32 v68, v194, v186
	s_nop 0
	v_cvt_pk_bf16_f32 v69, v195, v196
	s_nop 0
	v_cvt_pk_bf16_f32 v70, v76, v77
	s_nop 0
	v_add_f32_e32 v73, v71, v73
	s_nop 0
	v_cvt_pk_bf16_f32 v71, v72, v71
	s_waitcnt lgkmcnt(3)
	v_mfma_f32_32x32x16_bf16 v[48:63], v[160:163], v[64:67], v[48:63]
	v_add_f32_e32 v187, v187, v73
	ds_read_b128 v[72:75], v208 offset:32
	ds_read_b128 v[76:79], v208 offset:4640
	ds_read_b128 v[160:163], v208 offset:9248
	ds_read_b128 v[210:213], v208 offset:13856
	s_nop 1
	v_exp_f32_e32 v186, v80
	v_exp_f32_e32 v193, v81
	s_waitcnt lgkmcnt(6)
	v_mfma_f32_32x32x16_bf16 v[32:47], v[214:217], v[64:67], v[32:47]
	s_waitcnt lgkmcnt(5)
	v_mfma_f32_32x32x16_bf16 v[16:31], v[218:221], v[64:67], v[16:31]
	s_waitcnt lgkmcnt(4)
	v_mfma_f32_32x32x16_bf16 v[0:15], v[222:225], v[64:67], v[0:15]
	s_waitcnt lgkmcnt(3)
	v_mfma_f32_32x32x16_bf16 v[48:63], v[72:75], v[68:71], v[48:63]
	v_exp_f32_e32 v195, v82
	v_add_u32_e32 v194, s72, v183
	v_exp_f32_e32 v196, v83
	ds_read_b128 v[64:67], v194
	ds_read_b128 v[214:217], v194 offset:32
	v_exp_f32_e32 v84, v84
	v_add_f32_e32 v72, 0, v186
	v_exp_f32_e32 v85, v85
	s_waitcnt lgkmcnt(4)
	v_mfma_f32_32x32x16_bf16 v[32:47], v[76:79], v[68:71], v[32:47]
	v_add_f32_e32 v72, v193, v72
	v_add_f32_e32 v72, v195, v72
	v_add_f32_e32 v72, v196, v72
	v_add_f32_e32 v72, v84, v72
	v_add_f32_e32 v197, v85, v72
	s_waitcnt lgkmcnt(3)
	v_mfma_f32_32x32x16_bf16 v[16:31], v[160:163], v[68:71], v[16:31]
	s_waitcnt lgkmcnt(2)
	v_mfma_f32_32x32x16_bf16 v[0:15], v[210:213], v[68:71], v[0:15]
	s_waitcnt lgkmcnt(1)
	v_mfma_f32_32x32x16_bf16 v[64:79], v[64:67], v[100:103], 0
	ds_read_b128 v[80:83], v194 offset:64
	s_waitcnt lgkmcnt(1)
	v_mfma_f32_32x32x16_bf16 v[64:79], v[214:217], v[104:107], v[64:79]
	ds_read_b128 v[160:163], v194 offset:96
	v_exp_f32_e32 v86, v86
	s_nop 0
	v_add_f32_e32 v197, v86, v197
	s_waitcnt lgkmcnt(1)
; #define LAS __attribute__((address_space(3)))
; template <int DQK, bool MLA> ...
;     ...
;         for (int kk = 0; kk < 2; ++kk) {
;             if (kk == 0) {
; #pragma unroll
;                 for (int d = 0; d < 4; ++d) vf1[d] = *(const LAS bf16x8*)(vb + d * 4608 + 32);
;             } else { const LAS unsigned char* ka = lds + kafter_ofs + r32 * KPITCH + hi * 16; kp0 = *(const LAS bf16x8*)(ka); kp1 = *(const LAS bf16x8*)(ka + 32); }
;             const bf16x8 pb = __builtin_bit_cast(bf16x8, kk ? pw1 : pw0);
; #pragma unroll
;             for (int d = 0; d < 4; ++d) {
;                 o[d] = __builtin_amdgcn_mfma_f32_32x32x16_bf16(kk ? vf1[d] : vf0[d], pb, o[d], 0, 0, 0);
;                 const int e = 4 * kk + d - 2;
;                 if (e >= 0) { const float x = __builtin_amdgcn_exp2f(b[e]); b[e] = x; rs_n += x; }
;             }
;             __builtin_amdgcn_sched_barrier(0);
;         }
;         rs_early = rs_n;
;     };
;     int kc = 0, kn = KT_BYTES, kn2 = 2 * KT_BYTES;
;     for (int t = 0; t < NT; ++t) {
;         const bool has_k2 = (t + 2 < NT), has_v1 = (t + 1 < NT), active = (t <= tmax_w);
;         const int vofs = 3 * KT_BYTES + (t & 1) * VT_BYTES;
;         if (has_k2) gload_k(t + 2);
;         if (has_v1) gload_v(t + 1);
;         if (active) substep(sX, sY, kc + 32 * KPITCH, vofs, 0, kn);
;         if (active) substep(sY, sX, kn, vofs, 1, kn + 32 * KPITCH);
;         if (has_k2) sts_k(kn2);
;         if (has_v1) sts_v((t + 1) & 1);
;         __syncthreads();
;         const int tmp = kc; kc = kn; kn = kn2; kn2 = tmp;
	v_mfma_f32_32x32x16_bf16 v[64:79], v[80:83], v[108:111], v[64:79]
	ds_read_b128 v[210:213], v194 offset:128
	v_exp_f32_e32 v83, v87
	s_nop 0
	v_cvt_pk_bf16_f32 v80, v186, v193
	s_nop 0
	v_cvt_pk_bf16_f32 v81, v195, v196
	s_nop 0
	v_cvt_pk_bf16_f32 v82, v84, v85
	s_nop 0
	v_add_f32_e32 v197, v83, v197
	s_nop 0
	v_cvt_pk_bf16_f32 v83, v86, v83
	s_waitcnt lgkmcnt(1)
	v_mfma_f32_32x32x16_bf16 v[64:79], v[160:163], v[112:115], v[64:79]
	ds_read_b128 v[84:87], v194 offset:160
	v_exp_f32_e32 v186, v88
	s_nop 0
	v_add_f32_e32 v88, v186, v197
	s_waitcnt lgkmcnt(1)
	v_mfma_f32_32x32x16_bf16 v[64:79], v[210:213], v[116:119], v[64:79]
	ds_read_b128 v[160:163], v194 offset:192
	v_exp_f32_e32 v196, v89
	s_nop 0
	v_add_f32_e32 v88, v196, v88
	s_waitcnt lgkmcnt(1)
	v_mfma_f32_32x32x16_bf16 v[64:79], v[84:87], v[120:123], v[64:79]
	ds_read_b128 v[210:213], v194 offset:224
	v_exp_f32_e32 v226, v90
	s_nop 0
	v_add_f32_e32 v193, v226, v88
	s_waitcnt lgkmcnt(1)
	v_mfma_f32_32x32x16_bf16 v[64:79], v[160:163], v[124:127], v[64:79]
	ds_read_b128 v[84:87], v194 offset:256
	s_waitcnt lgkmcnt(1)
	v_mfma_f32_32x32x16_bf16 v[64:79], v[210:213], v[128:131], v[64:79]
	ds_read_b128 v[160:163], v194 offset:288
	v_exp_f32_e32 v195, v91
	s_waitcnt lgkmcnt(1)
	v_mfma_f32_32x32x16_bf16 v[64:79], v[84:87], v[136:139], v[64:79]
	ds_read_b128 v[88:91], v194 offset:320
	v_exp_f32_e32 v197, v92
	ds_read_b128 v[84:87], v194 offset:352
	ds_read_b128 v[210:213], v208 offset:64
	ds_read_b128 v[214:217], v208 offset:4672
	ds_read_b128 v[218:221], v208 offset:9280
	ds_read_b128 v[222:225], v208 offset:13888
	s_waitcnt lgkmcnt(6)
	v_mfma_f32_32x32x16_bf16 v[64:79], v[160:163], v[144:147], v[64:79]
	v_exp_f32_e32 v209, v93
	s_waitcnt lgkmcnt(5)
	v_mfma_f32_32x32x16_bf16 v[64:79], v[88:91], v[132:135], v[64:79]
	v_exp_f32_e32 v227, v94
	s_waitcnt lgkmcnt(4)
	v_mfma_f32_32x32x16_bf16 v[64:79], v[84:87], v[140:143], v[64:79]
	v_exp_f32_e32 v229, v95
	s_nop 0
	v_cvt_pk_bf16_f32 v84, v186, v196
	s_nop 0
	v_cvt_pk_bf16_f32 v85, v226, v195
	s_nop 0
	v_cvt_pk_bf16_f32 v86, v197, v209
	s_nop 0
	v_cvt_pk_bf16_f32 v87, v227, v229
	s_waitcnt lgkmcnt(3)
	v_mfma_f32_32x32x16_bf16 v[48:63], v[210:213], v[80:83], v[48:63]
	s_add_i32 s98, s68, 1
	s_bitcmp1_b32 s98, 0
	s_cselect_b32 s98, 0x4800, 0
	v_add_u32_e32 v230, s71, v172
	v_add_u32_e32 v231, s71, v174
	v_add_u32_e32 v232, s71, v184
	v_add_u32_e32 v233, s98, v173
	s_waitcnt vmcnt(4)
	ds_write_b128 v230, v[148:151]
	v_exp_f32_e32 v64, v64
	v_exp_f32_e32 v65, v65
	s_waitcnt lgkmcnt(3)
	v_mfma_f32_32x32x16_bf16 v[32:47], v[214:217], v[80:83], v[32:47]
	ds_read_b128 v[88:91], v208 offset:96
	ds_read_b128 v[92:95], v208 offset:4704
	ds_read_b128 v[210:213], v208 offset:9312
	ds_read_b128 v[214:217], v208 offset:13920
	s_waitcnt lgkmcnt(6)
	v_mfma_f32_32x32x16_bf16 v[16:31], v[218:221], v[80:83], v[16:31]
	s_waitcnt vmcnt(3)
	ds_write_b128 v231, v[152:155]
	s_waitcnt lgkmcnt(6)
	v_mfma_f32_32x32x16_bf16 v[0:15], v[222:225], v[80:83], v[0:15]
	v_exp_f32_e32 v66, v66
	s_waitcnt vmcnt(2)
	ds_write_b128 v232, v[156:159] offset:256
	s_waitcnt lgkmcnt(5)
	v_mfma_f32_32x32x16_bf16 v[48:63], v[88:91], v[84:87], v[48:63]
	v_exp_f32_e32 v67, v67
	ds_read_b128 v[80:83], v194 offset:12800
	ds_read_b128 v[160:163], v194 offset:12832
	v_exp_f32_e32 v68, v68
	v_mov_b32_e32 v194, v64
	v_exp_f32_e32 v69, v69
	v_pk_add_f32 v[88:89], v[194:195], v[192:193]
	v_mov_b32_e32 v196, v65
	s_waitcnt lgkmcnt(6)
	v_mfma_f32_32x32x16_bf16 v[32:47], v[92:95], v[84:87], v[32:47]
	v_add_f32_e64 v88, v196, v88
	v_add_f32_e64 v89, v197, v89
	v_mov_b32_e32 v208, v66
	v_add_f32_e64 v88, v208, v88
	v_add_f32_e64 v89, v209, v89
	v_mov_b32_e32 v226, v67
	v_pk_add_f32 v[88:89], v[226:227], v[88:89]
	v_mov_b32_e32 v228, v68
	v_pk_add_f32 v[88:89], v[228:229], v[88:89]
	s_waitcnt vmcnt(1)
	ds_write_b128 v233, v[164:167]
	s_waitcnt lgkmcnt(6)
	v_mfma_f32_32x32x16_bf16 v[16:31], v[210:213], v[84:87], v[16:31]
	v_mov_b32_e32 v186, v69
	v_add_f32_e64 v186, v186, v88
	v_add_f32_e64 v187, v187, v89
	s_waitcnt vmcnt(0)
	ds_write_b128 v233, v[168:171] offset:8192
	s_waitcnt lgkmcnt(6)
	v_mfma_f32_32x32x16_bf16 v[0:15], v[214:217], v[84:87], v[0:15]
	s_add_i32 s68, s68, 1
	s_add_i32 s73, s71, 0
	s_bitcmp1_b32 s68, 0
	s_cselect_b64 s[34:35], -1, 0
	s_and_b64 s[66:67], s[34:35], exec
	s_cselect_b32 s66, 0x4800, 0
	s_and_saveexec_b64 s[66:67], s[4:5]
	ds_write_b128 v233, v[96:99] offset:16384
	s_or_b64 exec, exec, s[66:67]
	s_branch .Lattn_wtail
.Lattn_inact:
	v_lshl_add_u64 v[84:85], s[26:27], 0, v[190:191]
	v_add_co_u32_e32 v88, vcc, 0x1d204000, v84
	v_lshl_add_u64 v[86:87], s[26:27], 0, v[202:203]
	s_nop 0
	v_addc_co_u32_e32 v89, vcc, 0, v85, vcc
	global_load_dwordx4 v[148:151], v[204:205], off
	global_load_dwordx4 v[152:155], v[206:207], off
	global_load_dwordx4 v[156:159], v[86:87], off
	global_load_dwordx4 v[164:167], v[88:89], off offset:2048
	v_add_co_u32_e32 v86, vcc, 0x1d206000, v84
	s_nop 0
	v_addc_co_u32_e32 v87, vcc, 0, v85, vcc
	global_load_dwordx4 v[168:171], v[86:87], off offset:2048
	s_and_saveexec_b64 s[34:35], s[4:5]
	s_cbranch_execz .LBB0_1043
	v_add_co_u32_e32 v84, vcc, 0x1d208000, v84
	s_nop 1
	v_addc_co_u32_e32 v85, vcc, 0, v85, vcc
	global_load_dwordx4 v[96:99], v[84:85], off offset:2048
.LBB0_1043:
	s_or_b64 exec, exec, s[34:35]
	s_add_i32 s68, s68, 1
	s_add_i32 s73, s71, 0
	s_bitcmp1_b32 s68, 0
	s_cselect_b64 s[34:35], -1, 0
	s_and_b64 s[66:67], s[34:35], exec
	v_add_u32_e32 v84, s73, v184
	v_add_u32_e32 v86, s73, v172
	s_cselect_b32 s66, 0x4800, 0
	v_add_u32_e32 v85, s73, v174
	s_waitcnt vmcnt(4)
	ds_write_b128 v86, v[148:151]
	s_waitcnt vmcnt(3)
	ds_write_b128 v85, v[152:155]
	s_waitcnt vmcnt(2)
	ds_write_b128 v84, v[156:159] offset:256
	v_add_u32_e32 v84, s66, v173
	s_waitcnt vmcnt(1)
	ds_write_b128 v84, v[164:167]
	s_waitcnt vmcnt(0)
	ds_write_b128 v84, v[168:171] offset:8192
	s_and_saveexec_b64 s[66:67], s[4:5]
	ds_write_b128 v84, v[96:99] offset:16384
	s_or_b64 exec, exec, s[66:67]
	v_lshl_add_u64 v[190:191], v[190:191], 0, s[20:21]
	v_lshl_add_u64 v[202:203], v[202:203], 0, s[0:1]
	v_lshl_add_u64 v[204:205], v[204:205], 0, s[14:15]
	v_lshl_add_u64 v[206:207], v[206:207], 0, s[14:15]
.Lattn_wtail:
	s_cmp_eq_u32 s49, s68
	s_waitcnt lgkmcnt(0)
	s_barrier
	s_cbranch_scc1 .LBB0_1049
	s_mov_b32 s34, s70
	s_mov_b32 s70, s72
	s_branch .LBB0_1041
